# speedup vs baseline: 1.0001x; 1.0001x over previous
; __device__ void attn_a_item(const Params& p, int layer, int b, int h, int q128, unsigned char* smem) {
;     ...
;     const bool young = __builtin_amdgcn_readfirstlane(tid_) >= 256;
;     if (young) __builtin_amdgcn_s_setprio(1);
.LBB0_264:
	v_readfirstlane_b32 s2, v189
	s_cmpk_lt_i32 s2, 0x100
	s_cbranch_scc0 .Lmy_noprio
	s_setprio 1
